# prep_item phase: half of each XCD's workgroups start ~half an item late so loads/stores of different workgroups interleave; on top of pipelined conv + prep prefetch
# baseline (speedup 1.0000x reference)
; #define LAS __attribute__((address_space(3)))
; __device__ __forceinline__ size_t PIX(int row, int col) { return (size_t)(col >> 7) * PSLOT + (size_t)row * 128 + (col & 127); }
; __device__ __forceinline__ int opaque_tid() { int t = threadIdx.x; asm volatile("" : "+v"(t)); return t; }
; __device__ void prep_item(const Params& p, int l, int item, LAS unsigned char* lds) {
;     const int tid = opaque_tid(), w = tid >> 6, lane = tid & 63;
;     const int tau = lane & 31, kh = lane >> 5, k0 = 16 * w + 8 * kh, l15 = lane & 15, q4 = lane >> 4;
;     const int ci = item % NCH, bh = item / NCH, h = bh & 3, b = bh >> 2;
;     const int R0 = ci < 8 ? NLAT + b * 256 + 32 * ci : b * 4096 + 32 * (ci - 8);
;     bf16_t* P = (bf16_t*)(p.ws + WS_BIG);
;     const bool first = (l == 0);
;     const bool want_out = first || ci >= 8;
;     for (int dd = 0; dd < 2; ++dd) { LAS unsigned* az = (LAS unsigned*)(lds + dd * P1_DIRSZ + P1_AW) + w * (32 * KT_ST / 2); for (int i = lane; i < 32 * KT_ST / 2; i += 64) az[i] = 0u; }
;     u32x4 rf0, rq0, rv0, rf1, rq1, rv1;
;     { const int r_ = R0 + tau; rf0 = *(const u32x4*)(P + PIX(r_, h * 128 + k0)); rq0 = *(const u32x4*)(P + PIX(r_, 1536 + h * 128 + k0)); rv0 = *(const u32x4*)(P + PIX(r_, 1024 + h * 128 + k0)); }
;     { const int r_ = R0 + 31 - tau; rf1 = *(const u32x4*)(P + PIX(r_, 512 + h * 128 + k0)); rq1 = *(const u32x4*)(P + PIX(r_, 1536 + h * 128 + k0)); rv1 = *(const u32x4*)(P + PIX(r_, 1024 + h * 128 + k0)); }
;     asm volatile("s_waitcnt vmcnt(0)" ::: "memory");
;     __syncthreads();
.Lpf_join_a:
	s_add_i32 s101, s101, s99
	s_mul_i32 s32, s100, 0x880000
	s_lshl_b32 s11, s101, 8
	s_add_u32 s32, s32, s11
	s_lshl_b32 s22, s100, 9
	s_add_u32 s18, s82, s32
	s_addc_u32 s19, s83, 0
	s_add_u32 s20, s18, 0x2200000
	s_addc_u32 s21, s19, 0
	s_add_u32 s98, s18, 0x4400000
	s_addc_u32 s99, s19, 0
	s_add_u32 s100, s18, 0x6600000
	s_addc_u32 s101, s19, 0
	global_load_dwordx4 v[188:191], v212, s[18:19]
	global_load_dwordx4 v[192:195], v212, s[100:101]
	global_load_dwordx4 v[196:199], v212, s[98:99]
	global_load_dwordx4 v[200:203], v213, s[20:21]
	global_load_dwordx4 v[204:207], v213, s[100:101]
	global_load_dwordx4 v[208:211], v213, s[98:99]
	s_add_u32 s18, s85, s22
	v_readlane_b32 s19, v243, 43
	s_nop 1
	s_addc_u32 s19, s19, 0
	s_nop 4
	global_load_dwordx4 v[216:219], v214, s[18:19]
	global_load_dwordx4 v[220:223], v214, s[18:19] offset:16
	global_load_dwordx4 v[224:227], v214, s[18:19] offset:2048
	global_load_dwordx4 v[228:231], v214, s[18:19] offset:2064
	s_waitcnt vmcnt(0)
	s_bitcmp1_b32 s92, 3
	s_cbranch_scc0 .Lprep_nostag
	s_sleep 90
.Lprep_nostag:
	s_branch .LBB0_243
